# baseline (speedup 1.0000x reference)
.LBB0_528:
	s_add_u32 s10, s70, s8
	s_addc_u32 s11, s71, s9
	s_add_u32 s10, s10, 0x100
	s_addc_u32 s11, s11, 0
	s_add_u32 s83, s80, s8
	s_addc_u32 s84, s81, s9
	s_add_i32 s85, 0, 0x10000
	s_cmpk_eq_i32 s8, 0x1500
	s_cselect_b32 s13, s1, s11
	s_cselect_b32 s12, s0, s10
	s_cselect_b32 s11, s45, s84
	s_cselect_b32 s10, s44, s83
	s_add_i32 s83, 0, 0x14000
	v_add_u32_e32 v154, s85, v140
	v_add_u32_e32 v172, s83, v140
	ds_read_b128 v[142:145], v154
	ds_read_b128 v[146:149], v154 offset:1024
	ds_read_b128 v[150:153], v154 offset:2048
	ds_read_b128 v[154:157], v154 offset:3072
	ds_read_b128 v[158:161], v172
	ds_read_b128 v[162:165], v172 offset:1024
	ds_read_b128 v[168:171], v172 offset:2048
	ds_read_b128 v[172:175], v172 offset:3072
	v_lshl_add_u64 v[184:185], v[138:139], 0, s[8:9]
	s_add_i32 m0, s36, 0xc000
	ds_read_b128 v[176:179], v141
	ds_read_b128 v[180:183], v141 offset:1024
	ds_read_b128 v[202:205], v141 offset:2048
	ds_read_b128 v[206:209], v141 offset:3072
	ds_read_b128 v[210:213], v141 offset:4096
	ds_read_b128 v[216:219], v141 offset:5120
	ds_read_b128 v[226:229], v141 offset:6144
	ds_read_b128 v[230:233], v141 offset:7168
	global_load_lds_dwordx4 v[184:185], off
	v_lshl_add_u64 v[184:185], v[136:137], 0, s[8:9]
	s_add_i32 m0, s36, 0xe000
	s_nop 0
	global_load_lds_dwordx4 v[184:185], off
	s_waitcnt vmcnt(8)
	s_waitcnt lgkmcnt(0)
	s_barrier
	s_setprio 1
	s_waitcnt lgkmcnt(0)
	v_mfma_f32_16x16x32_bf16 v[66:69], v[142:145], v[176:179], v[66:69]
	v_mfma_f32_16x16x32_bf16 v[34:37], v[150:153], v[176:179], v[34:37]
	v_mfma_f32_16x16x32_bf16 v[78:81], v[142:145], v[202:205], v[78:81]
	v_mfma_f32_16x16x32_bf16 v[46:49], v[150:153], v[202:205], v[46:49]
	v_mfma_f32_16x16x32_bf16 v[106:109], v[142:145], v[210:213], v[106:109]
	v_mfma_f32_16x16x32_bf16 v[62:65], v[150:153], v[210:213], v[62:65]
	v_mfma_f32_16x16x32_bf16 v[118:121], v[142:145], v[226:229], v[118:121]
	v_mfma_f32_16x16x32_bf16 v[74:77], v[150:153], v[226:229], v[74:77]
	v_mfma_f32_16x16x32_bf16 v[66:69], v[146:149], v[180:183], v[66:69]
	v_mfma_f32_16x16x32_bf16 v[34:37], v[154:157], v[180:183], v[34:37]
	v_mfma_f32_16x16x32_bf16 v[78:81], v[146:149], v[206:209], v[78:81]
	v_mfma_f32_16x16x32_bf16 v[46:49], v[154:157], v[206:209], v[46:49]
	v_mfma_f32_16x16x32_bf16 v[106:109], v[146:149], v[216:219], v[106:109]
	v_mfma_f32_16x16x32_bf16 v[62:65], v[154:157], v[216:219], v[62:65]
	v_mfma_f32_16x16x32_bf16 v[118:121], v[146:149], v[230:233], v[118:121]
	v_mfma_f32_16x16x32_bf16 v[74:77], v[154:157], v[230:233], v[74:77]
	v_mfma_f32_16x16x32_bf16 v[14:17], v[158:161], v[176:179], v[14:17]
	v_mfma_f32_16x16x32_bf16 v[2:5], v[168:171], v[176:179], v[2:5]
	v_mfma_f32_16x16x32_bf16 v[22:25], v[158:161], v[202:205], v[22:25]
	v_mfma_f32_16x16x32_bf16 v[6:9], v[168:171], v[202:205], v[6:9]
	v_mfma_f32_16x16x32_bf16 v[30:33], v[158:161], v[210:213], v[30:33]
	v_mfma_f32_16x16x32_bf16 v[10:13], v[168:171], v[210:213], v[10:13]
	v_mfma_f32_16x16x32_bf16 v[42:45], v[158:161], v[226:229], v[42:45]
	v_mfma_f32_16x16x32_bf16 v[18:21], v[168:171], v[226:229], v[18:21]
	v_mfma_f32_16x16x32_bf16 v[14:17], v[162:165], v[180:183], v[14:17]
	v_mfma_f32_16x16x32_bf16 v[2:5], v[172:175], v[180:183], v[2:5]
	v_mfma_f32_16x16x32_bf16 v[22:25], v[162:165], v[206:209], v[22:25]
	v_mfma_f32_16x16x32_bf16 v[6:9], v[172:175], v[206:209], v[6:9]
	v_mfma_f32_16x16x32_bf16 v[30:33], v[162:165], v[216:219], v[30:33]
	v_mfma_f32_16x16x32_bf16 v[10:13], v[172:175], v[216:219], v[10:13]
	v_mfma_f32_16x16x32_bf16 v[42:45], v[162:165], v[230:233], v[42:45]
	v_mfma_f32_16x16x32_bf16 v[18:21], v[172:175], v[230:233], v[18:21]
	s_setprio 0
	s_barrier
	s_add_i32 s84, s85, s24
	v_lshl_add_u64 v[184:185], s[10:11], 0, v[188:189]
	s_mov_b32 m0, s84
	ds_read_b128 v[176:179], v141 offset:16384
	ds_read_b128 v[180:183], v141 offset:17408
	ds_read_b128 v[202:205], v141 offset:18432
	ds_read_b128 v[206:209], v141 offset:19456
	ds_read_b128 v[210:213], v141 offset:20480
	ds_read_b128 v[216:219], v141 offset:21504
	ds_read_b128 v[226:229], v141 offset:22528
	ds_read_b128 v[230:233], v141 offset:23552
	global_load_lds_dwordx4 v[184:185], off
	s_add_i32 m0, s84, 0x2000
	s_add_u32 s84, s10, 0xb0000
	v_lshl_add_u64 v[234:235], s[10:11], 0, v[130:131]
	s_addc_u32 s85, s11, 0
	s_add_i32 s83, s83, s24
	global_load_lds_dwordx4 v[234:235], off
	v_lshl_add_u64 v[236:237], s[84:85], 0, v[188:189]
	s_mov_b32 m0, s83
	v_lshl_add_u64 v[238:239], s[12:13], 0, v[130:131]
	global_load_lds_dwordx4 v[236:237], off
	v_lshl_add_u64 v[236:237], s[84:85], 0, v[130:131]
	s_add_i32 m0, s83, 0x2000
	s_nop 0
	global_load_lds_dwordx4 v[236:237], off
	v_lshl_add_u64 v[236:237], s[12:13], 0, v[188:189]
	s_mov_b32 m0, s36
	s_nop 0
	global_load_lds_dwordx4 v[236:237], off
	s_mov_b32 m0, s37
	s_nop 0
	global_load_lds_dwordx4 v[238:239], off
	s_waitcnt vmcnt(8)
	s_waitcnt lgkmcnt(0)
	s_barrier
	s_setprio 1
	s_waitcnt lgkmcnt(0)
	v_mfma_f32_16x16x32_bf16 v[126:129], v[142:145], v[176:179], v[126:129]
	v_mfma_f32_16x16x32_bf16 v[98:101], v[150:153], v[176:179], v[98:101]
	v_mfma_f32_16x16x32_bf16 v[122:125], v[142:145], v[202:205], v[122:125]
	v_mfma_f32_16x16x32_bf16 v[114:117], v[150:153], v[202:205], v[114:117]
	v_mfma_f32_16x16x32_bf16 v[110:113], v[142:145], v[210:213], v[110:113]
	v_mfma_f32_16x16x32_bf16 v[102:105], v[150:153], v[210:213], v[102:105]
	v_mfma_f32_16x16x32_bf16 v[94:97], v[142:145], v[226:229], v[94:97]
	v_mfma_f32_16x16x32_bf16 v[90:93], v[150:153], v[226:229], v[90:93]
	v_mfma_f32_16x16x32_bf16 v[126:129], v[146:149], v[180:183], v[126:129]
	v_mfma_f32_16x16x32_bf16 v[98:101], v[154:157], v[180:183], v[98:101]
	v_mfma_f32_16x16x32_bf16 v[122:125], v[146:149], v[206:209], v[122:125]
	v_mfma_f32_16x16x32_bf16 v[114:117], v[154:157], v[206:209], v[114:117]
	v_mfma_f32_16x16x32_bf16 v[110:113], v[146:149], v[216:219], v[110:113]
	v_mfma_f32_16x16x32_bf16 v[102:105], v[154:157], v[216:219], v[102:105]
	v_mfma_f32_16x16x32_bf16 v[94:97], v[146:149], v[230:233], v[94:97]
	v_mfma_f32_16x16x32_bf16 v[90:93], v[154:157], v[230:233], v[90:93]
	v_mfma_f32_16x16x32_bf16 v[58:61], v[158:161], v[176:179], v[58:61]
	v_mfma_f32_16x16x32_bf16 v[26:29], v[168:171], v[176:179], v[26:29]
	v_mfma_f32_16x16x32_bf16 v[70:73], v[158:161], v[202:205], v[70:73]
	v_mfma_f32_16x16x32_bf16 v[38:41], v[168:171], v[202:205], v[38:41]
	v_mfma_f32_16x16x32_bf16 v[86:89], v[158:161], v[210:213], v[86:89]
	v_mfma_f32_16x16x32_bf16 v[54:57], v[168:171], v[210:213], v[54:57]
	v_mfma_f32_16x16x32_bf16 v[82:85], v[158:161], v[226:229], v[82:85]
	v_mfma_f32_16x16x32_bf16 v[50:53], v[168:171], v[226:229], v[50:53]
	v_mfma_f32_16x16x32_bf16 v[58:61], v[162:165], v[180:183], v[58:61]
	v_mfma_f32_16x16x32_bf16 v[26:29], v[172:175], v[180:183], v[26:29]
	v_mfma_f32_16x16x32_bf16 v[70:73], v[162:165], v[206:209], v[70:73]
	v_mfma_f32_16x16x32_bf16 v[38:41], v[172:175], v[206:209], v[38:41]
	v_mfma_f32_16x16x32_bf16 v[86:89], v[162:165], v[216:219], v[86:89]
	v_mfma_f32_16x16x32_bf16 v[54:57], v[172:175], v[216:219], v[54:57]
	v_mfma_f32_16x16x32_bf16 v[82:85], v[162:165], v[230:233], v[82:85]
	v_mfma_f32_16x16x32_bf16 v[50:53], v[172:175], v[230:233], v[50:53]
	s_setprio 0
	s_barrier
	s_add_i32 s83, 0, 0x18000
	s_add_i32 s84, 0, 0x1c000
	v_add_u32_e32 v154, s83, v140
	v_add_u32_e32 v172, s84, v140
	ds_read_b128 v[142:145], v154
	ds_read_b128 v[146:149], v154 offset:1024
	ds_read_b128 v[150:153], v154 offset:2048
	ds_read_b128 v[154:157], v154 offset:3072
	ds_read_b128 v[158:161], v172
	ds_read_b128 v[162:165], v172 offset:1024
	ds_read_b128 v[168:171], v172 offset:2048
	ds_read_b128 v[172:175], v172 offset:3072
	s_add_u32 s12, s12, 0xb0000
	s_addc_u32 s13, s13, 0
	s_mov_b32 m0, s54
	v_lshl_add_u64 v[240:241], s[12:13], 0, v[188:189]
	ds_read_b128 v[176:179], v141 offset:32768
	ds_read_b128 v[180:183], v141 offset:33792
	ds_read_b128 v[202:205], v141 offset:34816
	ds_read_b128 v[206:209], v141 offset:35840
	ds_read_b128 v[210:213], v141 offset:36864
	ds_read_b128 v[216:219], v141 offset:37888
	ds_read_b128 v[226:229], v141 offset:38912
	ds_read_b128 v[230:233], v141 offset:39936
	global_load_lds_dwordx4 v[240:241], off
	v_lshl_add_u64 v[240:241], s[12:13], 0, v[130:131]
	s_mov_b32 m0, s55
	s_nop 0
	global_load_lds_dwordx4 v[240:241], off
	s_waitcnt vmcnt(8)
	s_waitcnt lgkmcnt(0)
	s_barrier
	s_setprio 1
	s_waitcnt lgkmcnt(0)
	v_mfma_f32_16x16x32_bf16 v[66:69], v[142:145], v[176:179], v[66:69]
	v_mfma_f32_16x16x32_bf16 v[34:37], v[150:153], v[176:179], v[34:37]
	v_mfma_f32_16x16x32_bf16 v[78:81], v[142:145], v[202:205], v[78:81]
	v_mfma_f32_16x16x32_bf16 v[46:49], v[150:153], v[202:205], v[46:49]
	v_mfma_f32_16x16x32_bf16 v[106:109], v[142:145], v[210:213], v[106:109]
	v_mfma_f32_16x16x32_bf16 v[62:65], v[150:153], v[210:213], v[62:65]
	v_mfma_f32_16x16x32_bf16 v[118:121], v[142:145], v[226:229], v[118:121]
	v_mfma_f32_16x16x32_bf16 v[74:77], v[150:153], v[226:229], v[74:77]
	v_mfma_f32_16x16x32_bf16 v[66:69], v[146:149], v[180:183], v[66:69]
	v_mfma_f32_16x16x32_bf16 v[34:37], v[154:157], v[180:183], v[34:37]
	v_mfma_f32_16x16x32_bf16 v[78:81], v[146:149], v[206:209], v[78:81]
	v_mfma_f32_16x16x32_bf16 v[46:49], v[154:157], v[206:209], v[46:49]
	v_mfma_f32_16x16x32_bf16 v[106:109], v[146:149], v[216:219], v[106:109]
	v_mfma_f32_16x16x32_bf16 v[62:65], v[154:157], v[216:219], v[62:65]
	v_mfma_f32_16x16x32_bf16 v[118:121], v[146:149], v[230:233], v[118:121]
	v_mfma_f32_16x16x32_bf16 v[74:77], v[154:157], v[230:233], v[74:77]
	v_mfma_f32_16x16x32_bf16 v[14:17], v[158:161], v[176:179], v[14:17]
	v_mfma_f32_16x16x32_bf16 v[2:5], v[168:171], v[176:179], v[2:5]
	v_mfma_f32_16x16x32_bf16 v[22:25], v[158:161], v[202:205], v[22:25]
	v_mfma_f32_16x16x32_bf16 v[6:9], v[168:171], v[202:205], v[6:9]
	v_mfma_f32_16x16x32_bf16 v[30:33], v[158:161], v[210:213], v[30:33]
	v_mfma_f32_16x16x32_bf16 v[10:13], v[168:171], v[210:213], v[10:13]
	v_mfma_f32_16x16x32_bf16 v[42:45], v[158:161], v[226:229], v[42:45]
	v_mfma_f32_16x16x32_bf16 v[18:21], v[168:171], v[226:229], v[18:21]
	v_mfma_f32_16x16x32_bf16 v[14:17], v[162:165], v[180:183], v[14:17]
	v_mfma_f32_16x16x32_bf16 v[2:5], v[172:175], v[180:183], v[2:5]
	v_mfma_f32_16x16x32_bf16 v[22:25], v[162:165], v[206:209], v[22:25]
	v_mfma_f32_16x16x32_bf16 v[6:9], v[172:175], v[206:209], v[6:9]
	v_mfma_f32_16x16x32_bf16 v[30:33], v[162:165], v[216:219], v[30:33]
	v_mfma_f32_16x16x32_bf16 v[10:13], v[172:175], v[216:219], v[10:13]
	v_mfma_f32_16x16x32_bf16 v[42:45], v[162:165], v[230:233], v[42:45]
	v_mfma_f32_16x16x32_bf16 v[18:21], v[172:175], v[230:233], v[18:21]
	s_setprio 0
	s_barrier
	s_add_i32 s12, s83, s24
	v_lshl_add_u64 v[184:185], v[184:185], 0, s[4:5]
	s_mov_b32 m0, s12
	ds_read_b128 v[176:179], v141 offset:49152
	ds_read_b128 v[180:183], v141 offset:50176
	ds_read_b128 v[202:205], v141 offset:51200
	ds_read_b128 v[206:209], v141 offset:52224
	ds_read_b128 v[210:213], v141 offset:53248
	ds_read_b128 v[216:219], v141 offset:54272
	ds_read_b128 v[226:229], v141 offset:55296
	ds_read_b128 v[230:233], v141 offset:56320
	global_load_lds_dwordx4 v[184:185], off
	s_add_i32 m0, s12, 0x2000
	s_add_u32 s10, s10, 0xb0080
	v_lshl_add_u64 v[184:185], v[234:235], 0, s[4:5]
	s_addc_u32 s11, s11, 0
	s_add_i32 s12, s84, s24
	global_load_lds_dwordx4 v[184:185], off
	v_lshl_add_u64 v[184:185], s[10:11], 0, v[188:189]
	s_mov_b32 m0, s12
	s_nop 0
	global_load_lds_dwordx4 v[184:185], off
	v_lshl_add_u64 v[184:185], s[10:11], 0, v[130:131]
	s_add_i32 m0, s12, 0x2000
	s_nop 0
	global_load_lds_dwordx4 v[184:185], off
	v_lshl_add_u64 v[184:185], v[236:237], 0, s[4:5]
	s_mov_b32 m0, s61
	s_nop 0
	global_load_lds_dwordx4 v[184:185], off
	v_lshl_add_u64 v[184:185], v[238:239], 0, s[4:5]
	s_mov_b32 m0, s63
	s_nop 0
	global_load_lds_dwordx4 v[184:185], off
	s_waitcnt vmcnt(8)
	s_waitcnt lgkmcnt(0)
	s_barrier
	s_setprio 1
	s_waitcnt lgkmcnt(0)
	v_mfma_f32_16x16x32_bf16 v[126:129], v[142:145], v[176:179], v[126:129]
	v_mfma_f32_16x16x32_bf16 v[98:101], v[150:153], v[176:179], v[98:101]
	v_mfma_f32_16x16x32_bf16 v[122:125], v[142:145], v[202:205], v[122:125]
	v_mfma_f32_16x16x32_bf16 v[114:117], v[150:153], v[202:205], v[114:117]
	v_mfma_f32_16x16x32_bf16 v[110:113], v[142:145], v[210:213], v[110:113]
	v_mfma_f32_16x16x32_bf16 v[102:105], v[150:153], v[210:213], v[102:105]
	v_mfma_f32_16x16x32_bf16 v[94:97], v[142:145], v[226:229], v[94:97]
	v_mfma_f32_16x16x32_bf16 v[90:93], v[150:153], v[226:229], v[90:93]
	v_mfma_f32_16x16x32_bf16 v[126:129], v[146:149], v[180:183], v[126:129]
	v_mfma_f32_16x16x32_bf16 v[98:101], v[154:157], v[180:183], v[98:101]
	v_mfma_f32_16x16x32_bf16 v[122:125], v[146:149], v[206:209], v[122:125]
	v_mfma_f32_16x16x32_bf16 v[114:117], v[154:157], v[206:209], v[114:117]
	v_mfma_f32_16x16x32_bf16 v[110:113], v[146:149], v[216:219], v[110:113]
	v_mfma_f32_16x16x32_bf16 v[102:105], v[154:157], v[216:219], v[102:105]
	v_mfma_f32_16x16x32_bf16 v[94:97], v[146:149], v[230:233], v[94:97]
	v_mfma_f32_16x16x32_bf16 v[90:93], v[154:157], v[230:233], v[90:93]
	v_mfma_f32_16x16x32_bf16 v[58:61], v[158:161], v[176:179], v[58:61]
	v_mfma_f32_16x16x32_bf16 v[26:29], v[168:171], v[176:179], v[26:29]
	v_mfma_f32_16x16x32_bf16 v[70:73], v[158:161], v[202:205], v[70:73]
	v_mfma_f32_16x16x32_bf16 v[38:41], v[168:171], v[202:205], v[38:41]
	v_mfma_f32_16x16x32_bf16 v[86:89], v[158:161], v[210:213], v[86:89]
	v_mfma_f32_16x16x32_bf16 v[54:57], v[168:171], v[210:213], v[54:57]
	v_mfma_f32_16x16x32_bf16 v[82:85], v[158:161], v[226:229], v[82:85]
	v_mfma_f32_16x16x32_bf16 v[50:53], v[168:171], v[226:229], v[50:53]
	v_mfma_f32_16x16x32_bf16 v[58:61], v[162:165], v[180:183], v[58:61]
	v_mfma_f32_16x16x32_bf16 v[26:29], v[172:175], v[180:183], v[26:29]
	v_mfma_f32_16x16x32_bf16 v[70:73], v[162:165], v[206:209], v[70:73]
	v_mfma_f32_16x16x32_bf16 v[38:41], v[172:175], v[206:209], v[38:41]
	v_mfma_f32_16x16x32_bf16 v[86:89], v[162:165], v[216:219], v[86:89]
	v_mfma_f32_16x16x32_bf16 v[54:57], v[172:175], v[216:219], v[54:57]
	v_mfma_f32_16x16x32_bf16 v[82:85], v[162:165], v[230:233], v[82:85]
	v_mfma_f32_16x16x32_bf16 v[50:53], v[172:175], v[230:233], v[50:53]
	s_setprio 0
	s_barrier
	s_add_i32 s82, s82, 2
	s_add_u32 s8, s8, 0x100
	s_addc_u32 s9, s9, 0
	s_cmp_gt_u32 s82, 41
	s_cbranch_scc0 .LBB0_528
	s_add_u32 s8, s80, 0xffffff00
	s_addc_u32 s9, s81, -1
	s_and_b64 vcc, exec, s[42:43]
	s_cbranch_vccnz .LBB0_531
	v_mov_b32_e32 v50, 0
	s_mov_b32 s60, s77
	s_mov_b32 s19, s78
	s_mov_b64 s[70:71], s[0:1]
	s_mov_b32 s68, s79
	v_mov_b64_e32 v[2:3], 0
	v_mov_b64_e32 v[4:5], 0
	v_mov_b64_e32 v[6:7], 0
	v_mov_b64_e32 v[8:9], 0
	v_mov_b64_e32 v[10:11], 0
	v_mov_b64_e32 v[12:13], 0
	v_mov_b64_e32 v[14:15], 0
	v_mov_b64_e32 v[16:17], 0
	v_mov_b64_e32 v[18:19], 0
	v_mov_b64_e32 v[20:21], 0
	v_mov_b64_e32 v[22:23], 0
	v_mov_b64_e32 v[24:25], 0
	v_mov_b64_e32 v[26:27], 0
	v_mov_b64_e32 v[28:29], 0
	v_mov_b64_e32 v[30:31], 0
	v_mov_b64_e32 v[32:33], 0
	v_mov_b64_e32 v[34:35], 0
	v_mov_b64_e32 v[36:37], 0
	v_mov_b64_e32 v[38:39], 0
	v_mov_b64_e32 v[40:41], 0
	v_mov_b64_e32 v[42:43], 0
	v_mov_b64_e32 v[44:45], 0
	v_mov_b64_e32 v[46:47], 0
	v_mov_b64_e32 v[48:49], 0
	v_mov_b64_e32 v[50:51], 0
	v_mov_b64_e32 v[52:53], 0
	v_mov_b64_e32 v[54:55], 0
	v_mov_b64_e32 v[56:57], 0
	v_mov_b64_e32 v[58:59], 0
	v_mov_b64_e32 v[60:61], 0
	v_mov_b64_e32 v[62:63], 0
	v_mov_b64_e32 v[64:65], 0
	v_mov_b64_e32 v[66:67], 0
	v_mov_b64_e32 v[68:69], 0
	v_mov_b64_e32 v[70:71], 0
	v_mov_b64_e32 v[72:73], 0
	v_mov_b64_e32 v[74:75], 0
	v_mov_b64_e32 v[76:77], 0
	v_mov_b64_e32 v[78:79], 0
	v_mov_b64_e32 v[80:81], 0
	v_mov_b64_e32 v[82:83], 0
	v_mov_b64_e32 v[84:85], 0
	v_mov_b64_e32 v[86:87], 0
	v_mov_b64_e32 v[88:89], 0
	v_mov_b64_e32 v[90:91], 0
	v_mov_b64_e32 v[92:93], 0
	v_mov_b64_e32 v[94:95], 0
	v_mov_b64_e32 v[96:97], 0
	v_mov_b64_e32 v[98:99], 0
	v_mov_b64_e32 v[100:101], 0
	v_mov_b64_e32 v[102:103], 0
	v_mov_b64_e32 v[104:105], 0
	v_mov_b64_e32 v[106:107], 0
	v_mov_b64_e32 v[108:109], 0
	v_mov_b64_e32 v[110:111], 0
	v_mov_b64_e32 v[112:113], 0
	v_mov_b64_e32 v[114:115], 0
	v_mov_b64_e32 v[116:117], 0
	v_mov_b64_e32 v[118:119], 0
	v_mov_b64_e32 v[120:121], 0
	v_mov_b64_e32 v[122:123], 0
	v_mov_b64_e32 v[124:125], 0
	v_mov_b64_e32 v[126:127], 0
	v_mov_b64_e32 v[128:129], 0
	s_branch .LBB0_532

.LBB0_3228:
	s_add_u32 s10, s52, s8
	s_addc_u32 s11, s53, s9
	s_add_u32 s10, s10, 0x100
	s_addc_u32 s11, s11, 0
	s_add_u32 s71, s63, s8
	s_addc_u32 s77, s64, s9
	s_add_i32 s78, 0, 0x10000
	s_cmpk_eq_i32 s8, 0x700
	s_cselect_b32 s13, s59, s11
	s_cselect_b32 s12, s65, s10
	s_cselect_b32 s11, s57, s77
	s_cselect_b32 s10, s68, s71
	s_add_i32 s71, 0, 0x14000
	v_add_u32_e32 v154, s78, v140
	v_add_u32_e32 v169, s71, v140
	ds_read_b128 v[142:145], v154
	ds_read_b128 v[146:149], v154 offset:1024
	ds_read_b128 v[150:153], v154 offset:2048
	ds_read_b128 v[154:157], v154 offset:3072
	ds_read_b128 v[158:161], v169
	ds_read_b128 v[162:165], v169 offset:1024
	ds_read_b128 v[170:173], v169 offset:2048
	ds_read_b128 v[174:177], v169 offset:3072
	v_lshl_add_u64 v[230:231], v[138:139], 0, s[8:9]
	s_add_i32 m0, s29, 0xc000
	ds_read_b128 v[178:181], v141
	ds_read_b128 v[182:185], v141 offset:1024
	ds_read_b128 v[200:203], v141 offset:2048
	ds_read_b128 v[204:207], v141 offset:3072
	ds_read_b128 v[208:211], v141 offset:4096
	ds_read_b128 v[212:215], v141 offset:5120
	ds_read_b128 v[216:219], v141 offset:6144
	ds_read_b128 v[226:229], v141 offset:7168
	global_load_lds_dwordx4 v[230:231], off
	v_lshl_add_u64 v[230:231], v[136:137], 0, s[8:9]
	s_add_i32 m0, s29, 0xe000
	s_nop 0
	global_load_lds_dwordx4 v[230:231], off
	s_waitcnt vmcnt(8)
	s_waitcnt lgkmcnt(0)
	s_barrier
	s_setprio 1
	s_waitcnt lgkmcnt(0)
	v_mfma_f32_16x16x32_bf16 v[126:129], v[142:145], v[178:181], v[126:129]
	v_mfma_f32_16x16x32_bf16 v[66:69], v[150:153], v[178:181], v[66:69]
	v_mfma_f32_16x16x32_bf16 v[122:125], v[142:145], v[200:203], v[122:125]
	v_mfma_f32_16x16x32_bf16 v[70:73], v[150:153], v[200:203], v[70:73]
	v_mfma_f32_16x16x32_bf16 v[118:121], v[142:145], v[208:211], v[118:121]
	v_mfma_f32_16x16x32_bf16 v[74:77], v[150:153], v[208:211], v[74:77]
	v_mfma_f32_16x16x32_bf16 v[114:117], v[142:145], v[216:219], v[114:117]
	v_mfma_f32_16x16x32_bf16 v[78:81], v[150:153], v[216:219], v[78:81]
	v_mfma_f32_16x16x32_bf16 v[126:129], v[146:149], v[182:185], v[126:129]
	v_mfma_f32_16x16x32_bf16 v[66:69], v[154:157], v[182:185], v[66:69]
	v_mfma_f32_16x16x32_bf16 v[122:125], v[146:149], v[204:207], v[122:125]
	v_mfma_f32_16x16x32_bf16 v[70:73], v[154:157], v[204:207], v[70:73]
	v_mfma_f32_16x16x32_bf16 v[118:121], v[146:149], v[212:215], v[118:121]
	v_mfma_f32_16x16x32_bf16 v[74:77], v[154:157], v[212:215], v[74:77]
	v_mfma_f32_16x16x32_bf16 v[114:117], v[146:149], v[226:229], v[114:117]
	v_mfma_f32_16x16x32_bf16 v[78:81], v[154:157], v[226:229], v[78:81]
	v_mfma_f32_16x16x32_bf16 v[34:37], v[158:161], v[178:181], v[34:37]
	v_mfma_f32_16x16x32_bf16 v[2:5], v[170:173], v[178:181], v[2:5]
	v_mfma_f32_16x16x32_bf16 v[38:41], v[158:161], v[200:203], v[38:41]
	v_mfma_f32_16x16x32_bf16 v[6:9], v[170:173], v[200:203], v[6:9]
	v_mfma_f32_16x16x32_bf16 v[42:45], v[158:161], v[208:211], v[42:45]
	v_mfma_f32_16x16x32_bf16 v[10:13], v[170:173], v[208:211], v[10:13]
	v_mfma_f32_16x16x32_bf16 v[46:49], v[158:161], v[216:219], v[46:49]
	v_mfma_f32_16x16x32_bf16 v[14:17], v[170:173], v[216:219], v[14:17]
	v_mfma_f32_16x16x32_bf16 v[34:37], v[162:165], v[182:185], v[34:37]
	v_mfma_f32_16x16x32_bf16 v[2:5], v[174:177], v[182:185], v[2:5]
	v_mfma_f32_16x16x32_bf16 v[38:41], v[162:165], v[204:207], v[38:41]
	v_mfma_f32_16x16x32_bf16 v[6:9], v[174:177], v[204:207], v[6:9]
	v_mfma_f32_16x16x32_bf16 v[42:45], v[162:165], v[212:215], v[42:45]
	v_mfma_f32_16x16x32_bf16 v[10:13], v[174:177], v[212:215], v[10:13]
	v_mfma_f32_16x16x32_bf16 v[46:49], v[162:165], v[226:229], v[46:49]
	v_mfma_f32_16x16x32_bf16 v[14:17], v[174:177], v[226:229], v[14:17]
	s_setprio 0
	s_barrier
	s_add_i32 s77, s78, s19
	v_lshl_add_u64 v[230:231], s[10:11], 0, v[188:189]
	s_mov_b32 m0, s77
	ds_read_b128 v[178:181], v141 offset:16384
	ds_read_b128 v[182:185], v141 offset:17408
	ds_read_b128 v[200:203], v141 offset:18432
	ds_read_b128 v[204:207], v141 offset:19456
	ds_read_b128 v[208:211], v141 offset:20480
	ds_read_b128 v[212:215], v141 offset:21504
	ds_read_b128 v[216:219], v141 offset:22528
	ds_read_b128 v[226:229], v141 offset:23552
	global_load_lds_dwordx4 v[230:231], off
	s_add_i32 m0, s77, 0x2000
	s_add_u32 s78, s10, 0x40000
	v_lshl_add_u64 v[232:233], s[10:11], 0, v[130:131]
	s_addc_u32 s79, s11, 0
	s_add_i32 s71, s71, s19
	global_load_lds_dwordx4 v[232:233], off
	v_lshl_add_u64 v[234:235], s[78:79], 0, v[188:189]
	s_mov_b32 m0, s71
	v_lshl_add_u64 v[236:237], s[12:13], 0, v[130:131]
	global_load_lds_dwordx4 v[234:235], off
	v_lshl_add_u64 v[234:235], s[78:79], 0, v[130:131]
	s_add_i32 m0, s71, 0x2000
	s_nop 0
	global_load_lds_dwordx4 v[234:235], off
	v_lshl_add_u64 v[234:235], s[12:13], 0, v[188:189]
	s_mov_b32 m0, s29
	s_nop 0
	global_load_lds_dwordx4 v[234:235], off
	s_mov_b32 m0, s34
	s_nop 0
	global_load_lds_dwordx4 v[236:237], off
	s_waitcnt vmcnt(8)
	s_waitcnt lgkmcnt(0)
	s_barrier
	s_setprio 1
	s_waitcnt lgkmcnt(0)
	v_mfma_f32_16x16x32_bf16 v[106:109], v[142:145], v[178:181], v[106:109]
	v_mfma_f32_16x16x32_bf16 v[82:85], v[150:153], v[178:181], v[82:85]
	v_mfma_f32_16x16x32_bf16 v[110:113], v[142:145], v[200:203], v[110:113]
	v_mfma_f32_16x16x32_bf16 v[86:89], v[150:153], v[200:203], v[86:89]
	v_mfma_f32_16x16x32_bf16 v[102:105], v[142:145], v[208:211], v[102:105]
	v_mfma_f32_16x16x32_bf16 v[90:93], v[150:153], v[208:211], v[90:93]
	v_mfma_f32_16x16x32_bf16 v[98:101], v[142:145], v[216:219], v[98:101]
	v_mfma_f32_16x16x32_bf16 v[94:97], v[150:153], v[216:219], v[94:97]
	v_mfma_f32_16x16x32_bf16 v[106:109], v[146:149], v[182:185], v[106:109]
	v_mfma_f32_16x16x32_bf16 v[82:85], v[154:157], v[182:185], v[82:85]
	v_mfma_f32_16x16x32_bf16 v[110:113], v[146:149], v[204:207], v[110:113]
	v_mfma_f32_16x16x32_bf16 v[86:89], v[154:157], v[204:207], v[86:89]
	v_mfma_f32_16x16x32_bf16 v[102:105], v[146:149], v[212:215], v[102:105]
	v_mfma_f32_16x16x32_bf16 v[90:93], v[154:157], v[212:215], v[90:93]
	v_mfma_f32_16x16x32_bf16 v[98:101], v[146:149], v[226:229], v[98:101]
	v_mfma_f32_16x16x32_bf16 v[94:97], v[154:157], v[226:229], v[94:97]
	v_mfma_f32_16x16x32_bf16 v[50:53], v[158:161], v[178:181], v[50:53]
	v_mfma_f32_16x16x32_bf16 v[18:21], v[170:173], v[178:181], v[18:21]
	v_mfma_f32_16x16x32_bf16 v[54:57], v[158:161], v[200:203], v[54:57]
	v_mfma_f32_16x16x32_bf16 v[22:25], v[170:173], v[200:203], v[22:25]
	v_mfma_f32_16x16x32_bf16 v[58:61], v[158:161], v[208:211], v[58:61]
	v_mfma_f32_16x16x32_bf16 v[26:29], v[170:173], v[208:211], v[26:29]
	v_mfma_f32_16x16x32_bf16 v[62:65], v[158:161], v[216:219], v[62:65]
	v_mfma_f32_16x16x32_bf16 v[30:33], v[170:173], v[216:219], v[30:33]
	v_mfma_f32_16x16x32_bf16 v[50:53], v[162:165], v[182:185], v[50:53]
	v_mfma_f32_16x16x32_bf16 v[18:21], v[174:177], v[182:185], v[18:21]
	v_mfma_f32_16x16x32_bf16 v[54:57], v[162:165], v[204:207], v[54:57]
	v_mfma_f32_16x16x32_bf16 v[22:25], v[174:177], v[204:207], v[22:25]
	v_mfma_f32_16x16x32_bf16 v[58:61], v[162:165], v[212:215], v[58:61]
	v_mfma_f32_16x16x32_bf16 v[26:29], v[174:177], v[212:215], v[26:29]
	v_mfma_f32_16x16x32_bf16 v[62:65], v[162:165], v[226:229], v[62:65]
	v_mfma_f32_16x16x32_bf16 v[30:33], v[174:177], v[226:229], v[30:33]
	s_setprio 0
	s_barrier
	s_add_i32 s71, 0, 0x18000
	s_add_i32 s77, 0, 0x1c000
	v_add_u32_e32 v154, s71, v140
	v_add_u32_e32 v169, s77, v140
	ds_read_b128 v[142:145], v154
	ds_read_b128 v[146:149], v154 offset:1024
	ds_read_b128 v[150:153], v154 offset:2048
	ds_read_b128 v[154:157], v154 offset:3072
	ds_read_b128 v[158:161], v169
	ds_read_b128 v[162:165], v169 offset:1024
	ds_read_b128 v[170:173], v169 offset:2048
	ds_read_b128 v[174:177], v169 offset:3072
	s_add_u32 s12, s12, 0x40000
	s_addc_u32 s13, s13, 0
	s_mov_b32 m0, s35
	v_lshl_add_u64 v[238:239], s[12:13], 0, v[188:189]
	ds_read_b128 v[178:181], v141 offset:32768
	ds_read_b128 v[182:185], v141 offset:33792
	ds_read_b128 v[200:203], v141 offset:34816
	ds_read_b128 v[204:207], v141 offset:35840
	ds_read_b128 v[208:211], v141 offset:36864
	ds_read_b128 v[212:215], v141 offset:37888
	ds_read_b128 v[216:219], v141 offset:38912
	ds_read_b128 v[226:229], v141 offset:39936
	global_load_lds_dwordx4 v[238:239], off
	v_lshl_add_u64 v[238:239], s[12:13], 0, v[130:131]
	s_mov_b32 m0, s36
	s_nop 0
	global_load_lds_dwordx4 v[238:239], off
	s_waitcnt vmcnt(8)
	s_waitcnt lgkmcnt(0)
	s_barrier
	s_setprio 1
	s_waitcnt lgkmcnt(0)
	v_mfma_f32_16x16x32_bf16 v[126:129], v[142:145], v[178:181], v[126:129]
	v_mfma_f32_16x16x32_bf16 v[66:69], v[150:153], v[178:181], v[66:69]
	v_mfma_f32_16x16x32_bf16 v[122:125], v[142:145], v[200:203], v[122:125]
	v_mfma_f32_16x16x32_bf16 v[70:73], v[150:153], v[200:203], v[70:73]
	v_mfma_f32_16x16x32_bf16 v[118:121], v[142:145], v[208:211], v[118:121]
	v_mfma_f32_16x16x32_bf16 v[74:77], v[150:153], v[208:211], v[74:77]
	v_mfma_f32_16x16x32_bf16 v[114:117], v[142:145], v[216:219], v[114:117]
	v_mfma_f32_16x16x32_bf16 v[78:81], v[150:153], v[216:219], v[78:81]
	v_mfma_f32_16x16x32_bf16 v[126:129], v[146:149], v[182:185], v[126:129]
	v_mfma_f32_16x16x32_bf16 v[66:69], v[154:157], v[182:185], v[66:69]
	v_mfma_f32_16x16x32_bf16 v[122:125], v[146:149], v[204:207], v[122:125]
	v_mfma_f32_16x16x32_bf16 v[70:73], v[154:157], v[204:207], v[70:73]
	v_mfma_f32_16x16x32_bf16 v[118:121], v[146:149], v[212:215], v[118:121]
	v_mfma_f32_16x16x32_bf16 v[74:77], v[154:157], v[212:215], v[74:77]
	v_mfma_f32_16x16x32_bf16 v[114:117], v[146:149], v[226:229], v[114:117]
	v_mfma_f32_16x16x32_bf16 v[78:81], v[154:157], v[226:229], v[78:81]
	v_mfma_f32_16x16x32_bf16 v[34:37], v[158:161], v[178:181], v[34:37]
	v_mfma_f32_16x16x32_bf16 v[2:5], v[170:173], v[178:181], v[2:5]
	v_mfma_f32_16x16x32_bf16 v[38:41], v[158:161], v[200:203], v[38:41]
	v_mfma_f32_16x16x32_bf16 v[6:9], v[170:173], v[200:203], v[6:9]
	v_mfma_f32_16x16x32_bf16 v[42:45], v[158:161], v[208:211], v[42:45]
	v_mfma_f32_16x16x32_bf16 v[10:13], v[170:173], v[208:211], v[10:13]
	v_mfma_f32_16x16x32_bf16 v[46:49], v[158:161], v[216:219], v[46:49]
	v_mfma_f32_16x16x32_bf16 v[14:17], v[170:173], v[216:219], v[14:17]
	v_mfma_f32_16x16x32_bf16 v[34:37], v[162:165], v[182:185], v[34:37]
	v_mfma_f32_16x16x32_bf16 v[2:5], v[174:177], v[182:185], v[2:5]
	v_mfma_f32_16x16x32_bf16 v[38:41], v[162:165], v[204:207], v[38:41]
	v_mfma_f32_16x16x32_bf16 v[6:9], v[174:177], v[204:207], v[6:9]
	v_mfma_f32_16x16x32_bf16 v[42:45], v[162:165], v[212:215], v[42:45]
	v_mfma_f32_16x16x32_bf16 v[10:13], v[174:177], v[212:215], v[10:13]
	v_mfma_f32_16x16x32_bf16 v[46:49], v[162:165], v[226:229], v[46:49]
	v_mfma_f32_16x16x32_bf16 v[14:17], v[174:177], v[226:229], v[14:17]
	s_setprio 0
	s_barrier
	s_add_i32 s12, s71, s19
	v_lshl_add_u64 v[230:231], v[230:231], 0, s[4:5]
	s_mov_b32 m0, s12
	ds_read_b128 v[178:181], v141 offset:49152
	ds_read_b128 v[182:185], v141 offset:50176
	ds_read_b128 v[200:203], v141 offset:51200
	ds_read_b128 v[204:207], v141 offset:52224
	ds_read_b128 v[208:211], v141 offset:53248
	ds_read_b128 v[212:215], v141 offset:54272
	ds_read_b128 v[216:219], v141 offset:55296
	ds_read_b128 v[226:229], v141 offset:56320
	global_load_lds_dwordx4 v[230:231], off
	s_add_i32 m0, s12, 0x2000
	s_add_u32 s10, s10, 0x40080
	v_lshl_add_u64 v[230:231], v[232:233], 0, s[4:5]
	s_addc_u32 s11, s11, 0
	s_add_i32 s12, s77, s19
	global_load_lds_dwordx4 v[230:231], off
	v_lshl_add_u64 v[230:231], s[10:11], 0, v[188:189]
	s_mov_b32 m0, s12
	s_nop 0
	global_load_lds_dwordx4 v[230:231], off
	v_lshl_add_u64 v[230:231], s[10:11], 0, v[130:131]
	s_add_i32 m0, s12, 0x2000
	s_nop 0
	global_load_lds_dwordx4 v[230:231], off
	v_lshl_add_u64 v[230:231], v[234:235], 0, s[4:5]
	s_mov_b32 m0, s37
	s_nop 0
	global_load_lds_dwordx4 v[230:231], off
	v_lshl_add_u64 v[230:231], v[236:237], 0, s[4:5]
	s_mov_b32 m0, s43
	s_nop 0
	global_load_lds_dwordx4 v[230:231], off
	s_waitcnt vmcnt(8)
	s_waitcnt lgkmcnt(0)
	s_barrier
	s_setprio 1
	s_waitcnt lgkmcnt(0)
	v_mfma_f32_16x16x32_bf16 v[106:109], v[142:145], v[178:181], v[106:109]
	v_mfma_f32_16x16x32_bf16 v[82:85], v[150:153], v[178:181], v[82:85]
	v_mfma_f32_16x16x32_bf16 v[110:113], v[142:145], v[200:203], v[110:113]
	v_mfma_f32_16x16x32_bf16 v[86:89], v[150:153], v[200:203], v[86:89]
	v_mfma_f32_16x16x32_bf16 v[102:105], v[142:145], v[208:211], v[102:105]
	v_mfma_f32_16x16x32_bf16 v[90:93], v[150:153], v[208:211], v[90:93]
	v_mfma_f32_16x16x32_bf16 v[98:101], v[142:145], v[216:219], v[98:101]
	v_mfma_f32_16x16x32_bf16 v[94:97], v[150:153], v[216:219], v[94:97]
	v_mfma_f32_16x16x32_bf16 v[106:109], v[146:149], v[182:185], v[106:109]
	v_mfma_f32_16x16x32_bf16 v[82:85], v[154:157], v[182:185], v[82:85]
	v_mfma_f32_16x16x32_bf16 v[110:113], v[146:149], v[204:207], v[110:113]
	v_mfma_f32_16x16x32_bf16 v[86:89], v[154:157], v[204:207], v[86:89]
	v_mfma_f32_16x16x32_bf16 v[102:105], v[146:149], v[212:215], v[102:105]
	v_mfma_f32_16x16x32_bf16 v[90:93], v[154:157], v[212:215], v[90:93]
	v_mfma_f32_16x16x32_bf16 v[98:101], v[146:149], v[226:229], v[98:101]
	v_mfma_f32_16x16x32_bf16 v[94:97], v[154:157], v[226:229], v[94:97]
	v_mfma_f32_16x16x32_bf16 v[50:53], v[158:161], v[178:181], v[50:53]
	v_mfma_f32_16x16x32_bf16 v[18:21], v[170:173], v[178:181], v[18:21]
	v_mfma_f32_16x16x32_bf16 v[54:57], v[158:161], v[200:203], v[54:57]
	v_mfma_f32_16x16x32_bf16 v[22:25], v[170:173], v[200:203], v[22:25]
	v_mfma_f32_16x16x32_bf16 v[58:61], v[158:161], v[208:211], v[58:61]
	v_mfma_f32_16x16x32_bf16 v[26:29], v[170:173], v[208:211], v[26:29]
	v_mfma_f32_16x16x32_bf16 v[62:65], v[158:161], v[216:219], v[62:65]
	v_mfma_f32_16x16x32_bf16 v[30:33], v[170:173], v[216:219], v[30:33]
	v_mfma_f32_16x16x32_bf16 v[50:53], v[162:165], v[182:185], v[50:53]
	v_mfma_f32_16x16x32_bf16 v[18:21], v[174:177], v[182:185], v[18:21]
	v_mfma_f32_16x16x32_bf16 v[54:57], v[162:165], v[204:207], v[54:57]
	v_mfma_f32_16x16x32_bf16 v[22:25], v[174:177], v[204:207], v[22:25]
	v_mfma_f32_16x16x32_bf16 v[58:61], v[162:165], v[212:215], v[58:61]
	v_mfma_f32_16x16x32_bf16 v[26:29], v[174:177], v[212:215], v[26:29]
	v_mfma_f32_16x16x32_bf16 v[62:65], v[162:165], v[226:229], v[62:65]
	v_mfma_f32_16x16x32_bf16 v[30:33], v[174:177], v[226:229], v[30:33]
	s_setprio 0
	s_barrier
	s_add_i32 s70, s70, 2
	s_add_u32 s8, s8, 0x100
	s_addc_u32 s9, s9, 0
	s_cmp_gt_u32 s70, 13
	s_cbranch_scc0 .LBB0_3228
	s_add_u32 s8, s63, 0xffffff00
	s_addc_u32 s9, s64, -1
	s_andn2_b64 vcc, exec, s[40:41]
	s_cbranch_vccnz .LBB0_3219
	v_mov_b32_e32 v30, 0
	s_mov_b32 s42, s56
	s_mov_b32 s16, s58
	s_mov_b64 s[52:53], s[0:1]
	s_mov_b32 s55, s62
	v_mov_b64_e32 v[2:3], 0
	v_mov_b64_e32 v[4:5], 0
	v_mov_b64_e32 v[6:7], 0
	v_mov_b64_e32 v[8:9], 0
	v_mov_b64_e32 v[10:11], 0
	v_mov_b64_e32 v[12:13], 0
	v_mov_b64_e32 v[14:15], 0
	v_mov_b64_e32 v[16:17], 0
	v_mov_b64_e32 v[18:19], 0
	v_mov_b64_e32 v[20:21], 0
	v_mov_b64_e32 v[22:23], 0
	v_mov_b64_e32 v[24:25], 0
	v_mov_b64_e32 v[26:27], 0
	v_mov_b64_e32 v[28:29], 0
	v_mov_b64_e32 v[30:31], 0
	v_mov_b64_e32 v[32:33], 0
	v_mov_b64_e32 v[34:35], 0
	v_mov_b64_e32 v[36:37], 0
	v_mov_b64_e32 v[38:39], 0
	v_mov_b64_e32 v[40:41], 0
	v_mov_b64_e32 v[42:43], 0
	v_mov_b64_e32 v[44:45], 0
	v_mov_b64_e32 v[46:47], 0
	v_mov_b64_e32 v[48:49], 0
	v_mov_b64_e32 v[50:51], 0
	v_mov_b64_e32 v[52:53], 0
	v_mov_b64_e32 v[54:55], 0
	v_mov_b64_e32 v[56:57], 0
	v_mov_b64_e32 v[58:59], 0
	v_mov_b64_e32 v[60:61], 0
	v_mov_b64_e32 v[62:63], 0
	v_mov_b64_e32 v[64:65], 0
	v_mov_b64_e32 v[66:67], 0
	v_mov_b64_e32 v[68:69], 0
	v_mov_b64_e32 v[70:71], 0
	v_mov_b64_e32 v[72:73], 0
	v_mov_b64_e32 v[74:75], 0
	v_mov_b64_e32 v[76:77], 0
	v_mov_b64_e32 v[78:79], 0
	v_mov_b64_e32 v[80:81], 0
	v_mov_b64_e32 v[82:83], 0
	v_mov_b64_e32 v[84:85], 0
	v_mov_b64_e32 v[86:87], 0
	v_mov_b64_e32 v[88:89], 0
	v_mov_b64_e32 v[90:91], 0
	v_mov_b64_e32 v[92:93], 0
	v_mov_b64_e32 v[94:95], 0
	v_mov_b64_e32 v[96:97], 0
	v_mov_b64_e32 v[98:99], 0
	v_mov_b64_e32 v[100:101], 0
	v_mov_b64_e32 v[102:103], 0
	v_mov_b64_e32 v[104:105], 0
	v_mov_b64_e32 v[106:107], 0
	v_mov_b64_e32 v[108:109], 0
	v_mov_b64_e32 v[110:111], 0
	v_mov_b64_e32 v[112:113], 0
	v_mov_b64_e32 v[114:115], 0
	v_mov_b64_e32 v[116:117], 0
	v_mov_b64_e32 v[118:119], 0
	v_mov_b64_e32 v[120:121], 0
	v_mov_b64_e32 v[122:123], 0
	v_mov_b64_e32 v[124:125], 0
	v_mov_b64_e32 v[126:127], 0
	v_mov_b64_e32 v[128:129], 0
	s_mov_b64 s[70:71], 0x20000
	s_andn2_b64 vcc, exec, s[38:39]
	s_cbranch_vccnz .LBB0_3220
